# hyena MFMA loop: static prio 1 for waves 0-3 (on top of v11)
# speedup vs baseline: 1.0052x; 1.0052x over previous
.LBB0_500:
	s_or_b64 exec, exec, s[0:1]
	v_and_b32_e32 v0, 31, v77
	s_ashr_i32 s4, s10, 2
	v_bfe_u32 v79, v77, 4, 1
	s_and_b32 s0, s4, -16
	v_bfi_b32 v80, -16, s4, v77
	v_lshlrev_b32_e32 v0, 2, v0
	v_bfe_u32 v78, v77, 5, 1
	v_mul_u32_u24_e32 v2, 0x5a00, v79
	v_mul_lo_u32 v3, v80, s57
	v_readlane_b32 s1, v253, 46
	v_sub_u32_e32 v4, 0, v0
	s_addk_i32 s0, 0xff81
	v_add3_u32 v81, s1, v2, v3
	v_lshl_add_u32 v4, v78, 5, v4
	s_lshl_b32 s1, s0, 8
	v_lshlrev_b32_e32 v3, 4, v78
	v_subrev_u32_e32 v4, s1, v4
	s_mul_i32 s1, s0, 0xffffff70
	v_add_u32_e32 v5, 0x8000, v4
	v_add3_u32 v6, v81, v3, s1
	s_waitcnt lgkmcnt(0)
	s_barrier
	ds_read2_b32 v[38:39], v5 offset0:63 offset1:65
	ds_read2_b32 v[40:41], v5 offset0:67 offset1:69
	ds_read2_b32 v[34:35], v5 offset0:47 offset1:49
	ds_read2_b32 v[36:37], v5 offset0:51 offset1:53
	ds_read_b128 v[70:73], v6 offset:2304
	ds_read_b128 v[58:61], v6 offset:2336
	ds_read_b128 v[50:53], v6 offset:2368
	ds_read_b128 v[46:49], v6 offset:2400
	ds_read2_b32 v[42:43], v5 offset0:31 offset1:33
	ds_read2_b32 v[44:45], v5 offset0:35 offset1:37
	ds_read2_b32 v[54:55], v5 offset0:15 offset1:17
	ds_read2_b32 v[56:57], v5 offset0:19 offset1:21
	v_add_u32_e32 v6, 0x7e00, v4
	v_add_u32_e32 v4, 0x7c00, v4
	ds_read2_b32 v[62:63], v6 offset0:127 offset1:129
	ds_read2_b32 v[64:65], v5 offset0:3 offset1:5
	ds_read2_b32 v[66:67], v4 offset0:239 offset1:241
	ds_read2_b32 v[68:69], v4 offset0:243 offset1:245
	s_or_b32 s1, s4, 15
	s_cmp_lt_i32 s0, s1
	v_mov_b32_e32 v33, 0
	s_cbranch_scc0 .LBB0_503
	v_readfirstlane_b32 s5, v77
	s_cmpk_lt_u32 s5, 0x100
	s_cbranch_scc0 .Lhy_prio_skip
	s_setprio 1
